# stack6 + LDS-DMA issue spread across QK^T and P.V sections, softmax completes by 12th P.V gap
# baseline (speedup 1.0000x reference)
.Li0_entry:
	v_add_u32_e32 v167, s79, v147
	v_add_u32_e32 v227, s79, v149
	v_add_u32_e32 v194, s79, v151
	v_add_u32_e32 v195, s79, v153
	ds_read_b128 v[64:67], v167
	ds_read_b128 v[188:191], v227
	ds_read_b128 v[228:231], v194
	s_waitcnt lgkmcnt(2)
	v_mfma_f32_32x32x16_bf16 v[64:79], v[64:67], v[80:83], 0
	s_waitcnt lgkmcnt(1)
	v_mfma_f32_32x32x16_bf16 v[64:79], v[188:191], v[84:87], v[64:79]
	ds_read_b128 v[188:191], v195
	s_mov_b64 s[54:55], 0xe404000
	s_add_i32 m0, s96, 0x8000
	v_lshl_add_u64 v[192:193], v[134:135], 0, s[54:55]
	s_nop 0
	global_load_lds_dwordx4 v[192:193], off
	v_cndmask_b32_e64 v173, v113, v121, s[2:3]
	v_cndmask_b32_e64 v172, v112, v120, s[2:3]
	v_cndmask_b32_e64 v177, v121, v113, s[2:3]
	v_cndmask_b32_e64 v176, v120, v112, s[2:3]
	s_waitcnt lgkmcnt(1)
	v_mfma_f32_32x32x16_bf16 v[64:79], v[228:231], v[88:91], v[64:79]
	ds_read_b128 v[228:231], v167 offset:128
	v_cndmask_b32_e64 v171, v119, v127, s[2:3]
	v_cndmask_b32_e64 v170, v118, v126, s[2:3]
	v_cndmask_b32_e64 v169, v117, v125, s[2:3]
	v_cndmask_b32_e64 v168, v116, v124, s[2:3]
	s_waitcnt lgkmcnt(1)
	v_mfma_f32_32x32x16_bf16 v[64:79], v[188:191], v[92:95], v[64:79]
	ds_read_b128 v[188:191], v227 offset:128
	s_mov_b64 s[54:55], 0xe406000
	s_add_i32 m0, s96, 0xa000
	v_lshl_add_u64 v[192:193], v[134:135], 0, s[54:55]
	s_nop 0
	global_load_lds_dwordx4 v[192:193], off
	v_cndmask_b32_e64 v175, v115, v123, s[2:3]
	v_cndmask_b32_e64 v174, v114, v122, s[2:3]
	v_cndmask_b32_e64 v127, v127, v119, s[2:3]
	v_cndmask_b32_e64 v126, v126, v118, s[2:3]
	s_waitcnt lgkmcnt(1)
	v_mfma_f32_32x32x16_bf16 v[64:79], v[228:231], v[96:99], v[64:79]
	ds_read_b128 v[228:231], v194 offset:128
	v_cndmask_b32_e64 v125, v125, v117, s[2:3]
	v_cndmask_b32_e64 v124, v124, v116, s[2:3]
	v_cndmask_b32_e64 v179, v123, v115, s[2:3]
	v_cndmask_b32_e64 v178, v122, v114, s[2:3]
	s_waitcnt lgkmcnt(1)
	v_mfma_f32_32x32x16_bf16 v[64:79], v[188:191], v[100:103], v[64:79]
	ds_read_b128 v[188:191], v195 offset:128
	s_mov_b64 s[54:55], 0xe804000
	s_add_i32 m0, s96, 0xc000
	v_lshl_add_u64 v[192:193], v[134:135], 0, s[54:55]
	s_nop 0
	global_load_lds_dwordx4 v[192:193], off
	ds_read_b64_tr_b16 v[180:181], v158 offset:0
	ds_read_b64_tr_b16 v[182:183], v158 offset:0x800
	ds_read_b64_tr_b16 v[184:185], v158 offset:0x1000
	ds_read_b64_tr_b16 v[186:187], v158 offset:0x1800
	s_waitcnt lgkmcnt(5)
	v_mfma_f32_32x32x16_bf16 v[64:79], v[228:231], v[104:107], v[64:79]
	v_max_f32_e32 v194, v166, v166
	v_max_f32_e32 v195, v164, v164
	v_max_f32_e32 v194, v195, v194
	v_sub_f32_e32 v195, v194, v165
	v_mul_f32_e32 v195, 0x3db504f3, v195
	v_cmp_ge_f32_e32 vcc, s88, v195
	s_waitcnt lgkmcnt(4)
	v_mfma_f32_32x32x16_bf16 v[64:79], v[188:191], v[108:111], v[64:79]
	s_cmp_eq_u64 vcc, exec
	s_cbranch_scc0 .Li0_fb
	v_mov_b32_e32 v166, v165
	s_sub_i32 s52, s83, 64
	s_cmp_le_i32 s52, s25
	s_cbranch_scc1 .Li0_sm
	s_nop 7
	v_add_u32_e32 v112, 0x5b, v162
	v_cmp_gt_u32_e32 vcc, s86, v112
	v_add_u32_e32 v112, s83, v163
	v_add_u32_e32 v112, 0xffffffa1, v112
	v_cndmask_b32_e32 v64, v141, v64, vcc
	v_cmp_lt_u32_e32 vcc, s87, v112
	v_add_u32_e32 v112, 0x59, v162
	s_nop 0
	v_cndmask_b32_e32 v65, v141, v65, vcc
	v_cmp_gt_u32_e32 vcc, s86, v112
	v_add_u32_e32 v112, 0x58, v162
	s_nop 0
	v_cndmask_b32_e32 v66, v141, v66, vcc
	v_cmp_gt_u32_e32 vcc, s86, v112
	v_add_u32_e32 v112, 0x53, v162
	s_nop 0
	v_cndmask_b32_e32 v67, v141, v67, vcc
	v_cmp_gt_u32_e32 vcc, s86, v112
	v_add_u32_e32 v112, 0x52, v162
	s_nop 0
	v_cndmask_b32_e32 v68, v141, v68, vcc
	v_cmp_gt_u32_e32 vcc, s86, v112
	v_add_u32_e32 v112, 0x51, v162
	s_nop 0
	v_cndmask_b32_e32 v69, v141, v69, vcc
	v_cmp_gt_u32_e32 vcc, s86, v112
	v_add_u32_e32 v112, 0x50, v162
	s_nop 0
	v_cndmask_b32_e32 v70, v141, v70, vcc
	v_cmp_gt_u32_e32 vcc, s86, v112
	v_add_u32_e32 v112, 0x4b, v162
	s_nop 0
	v_cndmask_b32_e32 v71, v141, v71, vcc
	v_cmp_gt_u32_e32 vcc, s86, v112
	v_add_u32_e32 v112, 0x4a, v162
	s_nop 0
	v_cndmask_b32_e32 v72, v141, v72, vcc
	v_cmp_gt_u32_e32 vcc, s86, v112
	v_add_u32_e32 v112, 0x49, v162
	s_nop 0
	v_cndmask_b32_e32 v73, v141, v73, vcc
	v_cmp_gt_u32_e32 vcc, s86, v112
	v_add_u32_e32 v112, 0x48, v162
	s_nop 0
	v_cndmask_b32_e32 v74, v141, v74, vcc
	v_cmp_gt_u32_e32 vcc, s86, v112
	v_add_u32_e32 v112, 0x43, v162
	s_nop 0
	v_cndmask_b32_e32 v75, v141, v75, vcc
	v_cmp_gt_u32_e32 vcc, s86, v112
	v_add_u32_e32 v112, 0x42, v162
	s_nop 0
	v_cndmask_b32_e32 v76, v141, v76, vcc
	v_cmp_gt_u32_e32 vcc, s86, v112
	v_add_u32_e32 v112, 0x41, v162
	s_nop 0
	v_cndmask_b32_e32 v77, v141, v77, vcc
	v_cmp_gt_u32_e32 vcc, s86, v112
	v_add_u32_e32 v112, 64, v162
	s_nop 0
	v_cndmask_b32_e32 v78, v141, v78, vcc
	v_cmp_gt_u32_e32 vcc, s86, v112
	s_nop 1
	v_cndmask_b32_e32 v79, v141, v79, vcc
.Li0_sm:
	ds_read_b64_tr_b16 v[188:189], v158 offset:0x2000
	ds_read_b64_tr_b16 v[190:191], v158 offset:0x2800
	ds_read_b64_tr_b16 v[192:193], v158 offset:0x3000
	ds_read_b64_tr_b16 v[194:195], v158 offset:0x3800
	s_waitcnt lgkmcnt(4)
	s_nop 1
	v_mfma_f32_32x32x16_bf16 v[48:63], v[176:179], v[180:183], v[48:63]
	ds_read_b64_tr_b16 v[180:181], v158 offset:0x200
	ds_read_b64_tr_b16 v[182:183], v158 offset:0xa00
	v_mul_f32_e32 v114, 0xbe0293ee, v166
	v_max_f32_e32 v112, v65, v65
	v_max_f32_e32 v113, v64, v64
	v_fmamk_f32 v64, v64, 0x3e0293ee, v114
	v_max_f32_e32 v112, v113, v112
	v_exp_f32_e32 v64, v64
	v_fmamk_f32 v65, v65, 0x3e0293ee, v114
	v_mfma_f32_32x32x16_bf16 v[48:63], v[124:127], v[184:187], v[48:63]
	ds_read_b64_tr_b16 v[184:185], v158 offset:0x1200
	ds_read_b64_tr_b16 v[186:187], v158 offset:0x1a00
	v_max3_f32 v112, v112, v66, v67
	v_exp_f32_e32 v65, v65
	v_fmamk_f32 v66, v66, 0x3e0293ee, v114
	v_exp_f32_e32 v66, v66
	v_fmamk_f32 v67, v67, 0x3e0293ee, v114
	v_max3_f32 v112, v112, v68, v69
	v_exp_f32_e32 v67, v67
	s_waitcnt lgkmcnt(6)
	v_mfma_f32_32x32x16_bf16 v[48:63], v[172:175], v[188:191], v[48:63]
	ds_read_b64_tr_b16 v[188:189], v158 offset:0x2200
	ds_read_b64_tr_b16 v[190:191], v158 offset:0x2a00
	s_mov_b64 s[54:55], 0xe806000
	s_add_i32 m0, s96, 0xe000
	v_lshl_add_u64 v[228:229], v[134:135], 0, s[54:55]
	s_nop 0
	global_load_lds_dwordx4 v[228:229], off
	v_fmamk_f32 v68, v68, 0x3e0293ee, v114
	v_add_f32_e32 v115, 0, v64
	v_exp_f32_e32 v68, v68
	v_fmamk_f32 v69, v69, 0x3e0293ee, v114
	v_max3_f32 v112, v112, v70, v71
	v_add_f32_e32 v115, v65, v115
	v_exp_f32_e32 v69, v69
	s_waitcnt lgkmcnt(6)
	v_mfma_f32_32x32x16_bf16 v[48:63], v[168:171], v[192:195], v[48:63]
	ds_read_b64_tr_b16 v[192:193], v158 offset:0x3200
	ds_read_b64_tr_b16 v[194:195], v158 offset:0x3a00
	v_fmamk_f32 v70, v70, 0x3e0293ee, v114
	v_add_f32_e32 v115, v66, v115
	v_exp_f32_e32 v70, v70
	v_fmamk_f32 v71, v71, 0x3e0293ee, v114
	v_max3_f32 v112, v112, v72, v73
	v_add_f32_e32 v115, v67, v115
	v_exp_f32_e32 v71, v71
	s_waitcnt lgkmcnt(0)
	v_mfma_f32_32x32x16_bf16 v[32:47], v[176:179], v[180:183], v[32:47]
	ds_read_b64_tr_b16 v[180:181], v158 offset:0x400
	ds_read_b64_tr_b16 v[182:183], v158 offset:0xc00
	v_fmamk_f32 v72, v72, 0x3e0293ee, v114
	v_add_f32_e32 v115, v68, v115
	v_exp_f32_e32 v72, v72
	v_fmamk_f32 v73, v73, 0x3e0293ee, v114
	v_max3_f32 v112, v112, v74, v75
	v_add_f32_e32 v115, v69, v115
	v_exp_f32_e32 v73, v73
	v_mfma_f32_32x32x16_bf16 v[32:47], v[124:127], v[184:187], v[32:47]
	ds_read_b64_tr_b16 v[184:185], v158 offset:0x1400
	ds_read_b64_tr_b16 v[186:187], v158 offset:0x1c00
	v_fmamk_f32 v74, v74, 0x3e0293ee, v114
	v_add_f32_e32 v115, v70, v115
	v_exp_f32_e32 v74, v74
	v_fmamk_f32 v75, v75, 0x3e0293ee, v114
	v_max3_f32 v112, v112, v76, v77
	v_add_f32_e32 v115, v71, v115
	v_exp_f32_e32 v75, v75
	v_mfma_f32_32x32x16_bf16 v[32:47], v[172:175], v[188:191], v[32:47]
	ds_read_b64_tr_b16 v[188:189], v158 offset:0x2400
	ds_read_b64_tr_b16 v[190:191], v158 offset:0x2c00
	s_cmp_gt_i32 s19, s18
	s_cbranch_scc1 .Li0_kskip
	v_lshl_add_u64 v[228:229], s[50:51], 0, v[130:131]
	s_mov_b64 s[54:55], 0xc408000
	s_mov_b32 m0, s97
	v_lshl_add_u64 v[228:229], v[228:229], 0, s[54:55]
	s_nop 0
	global_load_lds_dwordx4 v[228:229], off
	v_lshl_add_u64 v[228:229], s[50:51], 0, v[130:131]
	s_mov_b64 s[54:55], 0xc40a000
	s_mov_b32 m0, s26
	v_lshl_add_u64 v[228:229], v[228:229], 0, s[54:55]
	s_nop 0
	global_load_lds_dwordx4 v[228:229], off
.Li0_kskip:
	v_fmamk_f32 v76, v76, 0x3e0293ee, v114
	v_add_f32_e32 v115, v72, v115
	v_exp_f32_e32 v76, v76
	v_fmamk_f32 v77, v77, 0x3e0293ee, v114
	v_max3_f32 v112, v112, v78, v79
	v_add_f32_e32 v115, v73, v115
	v_exp_f32_e32 v77, v77
	v_mfma_f32_32x32x16_bf16 v[32:47], v[168:171], v[192:195], v[32:47]
	ds_read_b64_tr_b16 v[192:193], v158 offset:0x3400
	ds_read_b64_tr_b16 v[194:195], v158 offset:0x3c00
	v_fmamk_f32 v78, v78, 0x3e0293ee, v114
	v_add_f32_e32 v115, v74, v115
	v_exp_f32_e32 v78, v78
	v_fmac_f32_e32 v114, 0x3e0293ee, v79
	v_add_f32_e32 v115, v75, v115
	v_exp_f32_e32 v79, v114
	v_add_f32_e32 v114, v76, v115
	s_waitcnt lgkmcnt(0)
	v_mfma_f32_32x32x16_bf16 v[16:31], v[176:179], v[180:183], v[16:31]
	ds_read_b64_tr_b16 v[180:181], v158 offset:0x600
	ds_read_b64_tr_b16 v[182:183], v158 offset:0xe00
	v_mov_b32_e32 v113, v112
	v_add_f32_e32 v114, v77, v114
	s_nop 0
	v_permlane32_swap_b32_e32 v112, v113
	v_add_f32_e32 v114, v78, v114
	v_add_f32_e32 v120, v79, v114
	v_max_f32_e32 v113, v113, v113
	v_max_f32_e32 v112, v112, v112
	v_mfma_f32_32x32x16_bf16 v[16:31], v[124:127], v[184:187], v[16:31]
	ds_read_b64_tr_b16 v[184:185], v158 offset:0x1600
	ds_read_b64_tr_b16 v[186:187], v158 offset:0x1e00
	v_max_f32_e32 v164, v112, v113
	v_mov_b32_e32 v121, v120
	v_cvt_pk_bf16_f32 v112, v64, v65
	v_cvt_pk_bf16_f32 v113, v66, v67
	v_cvt_pk_bf16_f32 v114, v68, v69
	v_cvt_pk_bf16_f32 v115, v70, v71
	v_cvt_pk_bf16_f32 v116, v72, v73
	v_mfma_f32_32x32x16_bf16 v[16:31], v[172:175], v[188:191], v[16:31]
	ds_read_b64_tr_b16 v[188:189], v158 offset:0x2600
	ds_read_b64_tr_b16 v[190:191], v158 offset:0x2e00
	v_cvt_pk_bf16_f32 v117, v74, v75
	v_cvt_pk_bf16_f32 v118, v76, v77
	v_cvt_pk_bf16_f32 v119, v78, v79
	s_nop 1
	v_permlane32_swap_b32_e32 v120, v121
	v_permlane32_swap_b32_e32 v112, v114
	v_permlane32_swap_b32_e32 v113, v115
	v_permlane32_swap_b32_e32 v116, v118
	v_mfma_f32_32x32x16_bf16 v[16:31], v[168:171], v[192:195], v[16:31]
	ds_read_b64_tr_b16 v[192:193], v158 offset:0x3600
	ds_read_b64_tr_b16 v[194:195], v158 offset:0x3e00
	v_permlane32_swap_b32_e32 v117, v119
	ds_write_b128 v157, v[112:115] offset:4096
	ds_write_b128 v157, v[116:119] offset:5120
	v_add_f32_e32 v120, v120, v121
	v_add_f32_e32 v155, v155, v120
	s_waitcnt lgkmcnt(0)
	v_mfma_f32_32x32x16_bf16 v[0:15], v[176:179], v[180:183], v[0:15]
	v_mfma_f32_32x32x16_bf16 v[0:15], v[124:127], v[184:187], v[0:15]
	v_mfma_f32_32x32x16_bf16 v[0:15], v[172:175], v[188:191], v[0:15]
	v_mfma_f32_32x32x16_bf16 v[0:15], v[168:171], v[192:195], v[0:15]
	s_and_saveexec_b64 s[52:53], s[4:5]
	ds_write_b32 v160, v164 offset:8448
	s_or_b64 exec, exec, s[52:53]
	s_waitcnt vmcnt(0)
	s_waitcnt vmcnt(0) lgkmcnt(0)
	s_barrier
	s_branch .LBB0_748

.Li1_entry:
	ds_read_b128 v[64:67], v148
	ds_read_b128 v[188:191], v150
	ds_read_b128 v[228:231], v152
	s_waitcnt lgkmcnt(2)
	v_mfma_f32_32x32x16_bf16 v[64:79], v[64:67], v[80:83], 0
	s_waitcnt lgkmcnt(1)
	v_mfma_f32_32x32x16_bf16 v[64:79], v[188:191], v[84:87], v[64:79]
	ds_read_b128 v[188:191], v154
	s_mov_b64 s[56:57], 0xe408000
	s_mov_b32 m0, s96
	v_lshl_add_u64 v[192:193], v[134:135], 0, s[56:57]
	s_nop 0
	global_load_lds_dwordx4 v[192:193], off
	v_cndmask_b32_e64 v173, v113, v121, s[2:3]
	v_cndmask_b32_e64 v172, v112, v120, s[2:3]
	v_cndmask_b32_e64 v177, v121, v113, s[2:3]
	v_cndmask_b32_e64 v176, v120, v112, s[2:3]
	s_waitcnt lgkmcnt(1)
	v_mfma_f32_32x32x16_bf16 v[64:79], v[228:231], v[88:91], v[64:79]
	ds_read_b128 v[228:231], v148 offset:128
	v_cndmask_b32_e64 v171, v127, v119, s[2:3]
	v_cndmask_b32_e64 v170, v126, v118, s[2:3]
	v_cndmask_b32_e64 v169, v125, v117, s[2:3]
	v_cndmask_b32_e64 v168, v124, v116, s[2:3]
	s_waitcnt lgkmcnt(1)
	v_mfma_f32_32x32x16_bf16 v[64:79], v[188:191], v[92:95], v[64:79]
	ds_read_b128 v[188:191], v150 offset:128
	s_mov_b64 s[56:57], 0xe40a000
	s_mov_b32 m0, s6
	v_lshl_add_u64 v[192:193], v[134:135], 0, s[56:57]
	s_nop 0
	global_load_lds_dwordx4 v[192:193], off
	v_cndmask_b32_e64 v175, v115, v123, s[2:3]
	v_cndmask_b32_e64 v174, v114, v122, s[2:3]
	v_cndmask_b32_e64 v127, v119, v127, s[2:3]
	v_cndmask_b32_e64 v126, v118, v126, s[2:3]
	s_waitcnt lgkmcnt(1)
	v_mfma_f32_32x32x16_bf16 v[64:79], v[228:231], v[96:99], v[64:79]
	ds_read_b128 v[228:231], v152 offset:128
	v_cndmask_b32_e64 v125, v117, v125, s[2:3]
	v_cndmask_b32_e64 v124, v116, v124, s[2:3]
	v_cndmask_b32_e64 v179, v123, v115, s[2:3]
	v_cndmask_b32_e64 v178, v122, v114, s[2:3]
	s_waitcnt lgkmcnt(1)
	v_mfma_f32_32x32x16_bf16 v[64:79], v[188:191], v[100:103], v[64:79]
	ds_read_b128 v[188:191], v154 offset:128
	s_mov_b64 s[56:57], 0xe808000
	s_mov_b32 m0, s7
	v_lshl_add_u64 v[192:193], v[134:135], 0, s[56:57]
	s_nop 0
	global_load_lds_dwordx4 v[192:193], off
	ds_read_b64_tr_b16 v[180:181], v158 offset:0x8000
	ds_read_b64_tr_b16 v[182:183], v158 offset:0x8800
	ds_read_b64_tr_b16 v[184:185], v158 offset:0x9000
	ds_read_b64_tr_b16 v[186:187], v158 offset:0x9800
	s_waitcnt lgkmcnt(5)
	v_mfma_f32_32x32x16_bf16 v[64:79], v[228:231], v[104:107], v[64:79]
	v_max_f32_e32 v194, v128, v128
	v_max_f32_e32 v195, v164, v164
	v_max_f32_e32 v194, v195, v194
	v_sub_f32_e32 v195, v194, v166
	v_mul_f32_e32 v195, 0x3db504f3, v195
	v_cmp_ge_f32_e32 vcc, s88, v195
	s_waitcnt lgkmcnt(4)
	v_mfma_f32_32x32x16_bf16 v[64:79], v[188:191], v[108:111], v[64:79]
	s_cmp_eq_u64 vcc, exec
	s_cbranch_scc0 .Li1_fb
	v_mov_b32_e32 v165, v166
	s_cmp_le_i32 s83, s25
	s_cbranch_scc1 .Li1_sm
	s_nop 7
	v_add_u32_e32 v112, 27, v162
	v_cmp_gt_u32_e32 vcc, s86, v112
	v_add_u32_e32 v112, s83, v163
	v_subrev_u32_e32 v112, 31, v112
	v_cndmask_b32_e32 v64, v141, v64, vcc
	v_cmp_lt_u32_e32 vcc, s87, v112
	v_add_u32_e32 v112, 25, v162
	s_nop 0
	v_cndmask_b32_e32 v65, v141, v65, vcc
	v_cmp_gt_u32_e32 vcc, s86, v112
	v_add_u32_e32 v112, 24, v162
	s_nop 0
	v_cndmask_b32_e32 v66, v141, v66, vcc
	v_cmp_gt_u32_e32 vcc, s86, v112
	v_add_u32_e32 v112, 19, v162
	s_nop 0
	v_cndmask_b32_e32 v67, v141, v67, vcc
	v_cmp_gt_u32_e32 vcc, s86, v112
	v_add_u32_e32 v112, 18, v162
	s_nop 0
	v_cndmask_b32_e32 v68, v141, v68, vcc
	v_cmp_gt_u32_e32 vcc, s86, v112
	v_add_u32_e32 v112, 17, v162
	s_nop 0
	v_cndmask_b32_e32 v69, v141, v69, vcc
	v_cmp_gt_u32_e32 vcc, s86, v112
	v_add_u32_e32 v112, 16, v162
	s_nop 0
	v_cndmask_b32_e32 v70, v141, v70, vcc
	v_cmp_gt_u32_e32 vcc, s86, v112
	v_add_u32_e32 v112, 11, v162
	s_nop 0
	v_cndmask_b32_e32 v71, v141, v71, vcc
	v_cmp_gt_u32_e32 vcc, s86, v112
	v_add_u32_e32 v112, 10, v162
	s_nop 0
	v_cndmask_b32_e32 v72, v141, v72, vcc
	v_cmp_gt_u32_e32 vcc, s86, v112
	v_add_u32_e32 v112, 9, v162
	s_nop 0
	v_cndmask_b32_e32 v73, v141, v73, vcc
	v_cmp_gt_u32_e32 vcc, s86, v112
	v_add_u32_e32 v112, 8, v162
	s_nop 0
	v_cndmask_b32_e32 v74, v141, v74, vcc
	v_cmp_gt_u32_e32 vcc, s86, v112
	v_add_u32_e32 v112, 3, v162
	s_nop 0
	v_cndmask_b32_e32 v75, v141, v75, vcc
	v_cmp_gt_u32_e32 vcc, s86, v112
	v_add_u32_e32 v112, 2, v162
	s_nop 0
	v_cndmask_b32_e32 v76, v141, v76, vcc
	v_cmp_gt_u32_e32 vcc, s86, v112
	v_add_u32_e32 v112, 1, v162
	s_nop 0
	v_cndmask_b32_e32 v77, v141, v77, vcc
	v_cmp_gt_u32_e32 vcc, s86, v112
	s_nop 1
	v_cndmask_b32_e32 v78, v141, v78, vcc
	v_cmp_gt_u32_e32 vcc, s86, v162
	s_nop 1
	v_cndmask_b32_e32 v79, v141, v79, vcc
.Li1_sm:
	ds_read_b64_tr_b16 v[188:189], v158 offset:0xa000
	ds_read_b64_tr_b16 v[190:191], v158 offset:0xa800
	ds_read_b64_tr_b16 v[192:193], v158 offset:0xb000
	ds_read_b64_tr_b16 v[194:195], v158 offset:0xb800
	s_waitcnt lgkmcnt(4)
	s_nop 1
	v_mfma_f32_32x32x16_bf16 v[48:63], v[176:179], v[180:183], v[48:63]
	ds_read_b64_tr_b16 v[180:181], v158 offset:0x8200
	ds_read_b64_tr_b16 v[182:183], v158 offset:0x8a00
	v_mul_f32_e32 v114, 0xbe0293ee, v165
	v_max_f32_e32 v112, v65, v65
	v_max_f32_e32 v113, v64, v64
	v_fmamk_f32 v64, v64, 0x3e0293ee, v114
	v_max_f32_e32 v112, v113, v112
	v_exp_f32_e32 v64, v64
	v_fmamk_f32 v65, v65, 0x3e0293ee, v114
	v_mfma_f32_32x32x16_bf16 v[48:63], v[168:171], v[184:187], v[48:63]
	ds_read_b64_tr_b16 v[184:185], v158 offset:0x9200
	ds_read_b64_tr_b16 v[186:187], v158 offset:0x9a00
	v_max3_f32 v112, v112, v66, v67
	v_exp_f32_e32 v65, v65
	v_fmamk_f32 v66, v66, 0x3e0293ee, v114
	v_exp_f32_e32 v66, v66
	v_fmamk_f32 v67, v67, 0x3e0293ee, v114
	v_max3_f32 v112, v112, v68, v69
	v_exp_f32_e32 v67, v67
	s_waitcnt lgkmcnt(6)
	v_mfma_f32_32x32x16_bf16 v[48:63], v[172:175], v[188:191], v[48:63]
	ds_read_b64_tr_b16 v[188:189], v158 offset:0xa200
	ds_read_b64_tr_b16 v[190:191], v158 offset:0xaa00
	s_mov_b64 s[56:57], 0xe80a000
	s_mov_b32 m0, s24
	v_lshl_add_u64 v[228:229], v[134:135], 0, s[56:57]
	s_nop 0
	global_load_lds_dwordx4 v[228:229], off
	v_fmamk_f32 v68, v68, 0x3e0293ee, v114
	v_add_f32_e32 v115, 0, v64
	v_exp_f32_e32 v68, v68
	v_fmamk_f32 v69, v69, 0x3e0293ee, v114
	v_max3_f32 v112, v112, v70, v71
	v_add_f32_e32 v115, v65, v115
	v_exp_f32_e32 v69, v69
	s_waitcnt lgkmcnt(6)
	v_mfma_f32_32x32x16_bf16 v[48:63], v[124:127], v[192:195], v[48:63]
	ds_read_b64_tr_b16 v[192:193], v158 offset:0xb200
	ds_read_b64_tr_b16 v[194:195], v158 offset:0xba00
	v_fmamk_f32 v70, v70, 0x3e0293ee, v114
	v_add_f32_e32 v115, v66, v115
	v_exp_f32_e32 v70, v70
	v_fmamk_f32 v71, v71, 0x3e0293ee, v114
	v_max3_f32 v112, v112, v72, v73
	v_add_f32_e32 v115, v67, v115
	v_exp_f32_e32 v71, v71
	s_waitcnt lgkmcnt(0)
	v_mfma_f32_32x32x16_bf16 v[32:47], v[176:179], v[180:183], v[32:47]
	ds_read_b64_tr_b16 v[180:181], v158 offset:0x8400
	ds_read_b64_tr_b16 v[182:183], v158 offset:0x8c00
	v_fmamk_f32 v72, v72, 0x3e0293ee, v114
	v_add_f32_e32 v115, v68, v115
	v_exp_f32_e32 v72, v72
	v_fmamk_f32 v73, v73, 0x3e0293ee, v114
	v_max3_f32 v112, v112, v74, v75
	v_add_f32_e32 v115, v69, v115
	v_exp_f32_e32 v73, v73
	v_mfma_f32_32x32x16_bf16 v[32:47], v[168:171], v[184:187], v[32:47]
	ds_read_b64_tr_b16 v[184:185], v158 offset:0x9400
	ds_read_b64_tr_b16 v[186:187], v158 offset:0x9c00
	v_fmamk_f32 v74, v74, 0x3e0293ee, v114
	v_add_f32_e32 v115, v70, v115
	v_exp_f32_e32 v74, v74
	v_fmamk_f32 v75, v75, 0x3e0293ee, v114
	v_max3_f32 v112, v112, v76, v77
	v_add_f32_e32 v115, v71, v115
	v_exp_f32_e32 v75, v75
	v_mfma_f32_32x32x16_bf16 v[32:47], v[172:175], v[188:191], v[32:47]
	ds_read_b64_tr_b16 v[188:189], v158 offset:0xa400
	ds_read_b64_tr_b16 v[190:191], v158 offset:0xac00
	s_add_i32 s56, s19, 1
	s_cmp_gt_i32 s56, s18
	s_cbranch_scc1 .Li1_kskip
	v_lshl_add_u64 v[228:229], s[50:51], 0, v[130:131]
	s_mov_b64 s[56:57], 0xc40c000
	s_mov_b32 m0, s27
	v_lshl_add_u64 v[228:229], v[228:229], 0, s[56:57]
	s_nop 0
	global_load_lds_dwordx4 v[228:229], off
	v_lshl_add_u64 v[228:229], s[50:51], 0, v[130:131]
	s_mov_b64 s[56:57], 0xc40e000
	s_mov_b32 m0, s62
	v_lshl_add_u64 v[228:229], v[228:229], 0, s[56:57]
	s_nop 0
	global_load_lds_dwordx4 v[228:229], off
.Li1_kskip:
	v_fmamk_f32 v76, v76, 0x3e0293ee, v114
	v_add_f32_e32 v115, v72, v115
	v_exp_f32_e32 v76, v76
	v_fmamk_f32 v77, v77, 0x3e0293ee, v114
	v_max3_f32 v112, v112, v78, v79
	v_add_f32_e32 v115, v73, v115
	v_exp_f32_e32 v77, v77
	v_mfma_f32_32x32x16_bf16 v[32:47], v[124:127], v[192:195], v[32:47]
	ds_read_b64_tr_b16 v[192:193], v158 offset:0xb400
	ds_read_b64_tr_b16 v[194:195], v158 offset:0xbc00
	v_fmamk_f32 v78, v78, 0x3e0293ee, v114
	v_add_f32_e32 v115, v74, v115
	v_exp_f32_e32 v78, v78
	v_fmac_f32_e32 v114, 0x3e0293ee, v79
	v_add_f32_e32 v115, v75, v115
	v_exp_f32_e32 v79, v114
	v_add_f32_e32 v114, v76, v115
	s_waitcnt lgkmcnt(0)
	v_mfma_f32_32x32x16_bf16 v[16:31], v[176:179], v[180:183], v[16:31]
	ds_read_b64_tr_b16 v[180:181], v158 offset:0x8600
	ds_read_b64_tr_b16 v[182:183], v158 offset:0x8e00
	v_mov_b32_e32 v113, v112
	v_add_f32_e32 v114, v77, v114
	s_nop 0
	v_permlane32_swap_b32_e32 v112, v113
	v_add_f32_e32 v114, v78, v114
	v_add_f32_e32 v120, v79, v114
	v_max_f32_e32 v113, v113, v113
	v_max_f32_e32 v112, v112, v112
	v_mfma_f32_32x32x16_bf16 v[16:31], v[168:171], v[184:187], v[16:31]
	ds_read_b64_tr_b16 v[184:185], v158 offset:0x9600
	ds_read_b64_tr_b16 v[186:187], v158 offset:0x9e00
	v_max_f32_e32 v164, v112, v113
	v_mov_b32_e32 v121, v120
	v_cvt_pk_bf16_f32 v112, v64, v65
	v_cvt_pk_bf16_f32 v113, v66, v67
	v_cvt_pk_bf16_f32 v114, v68, v69
	v_cvt_pk_bf16_f32 v115, v70, v71
	v_cvt_pk_bf16_f32 v116, v72, v73
	v_mfma_f32_32x32x16_bf16 v[16:31], v[172:175], v[188:191], v[16:31]
	ds_read_b64_tr_b16 v[188:189], v158 offset:0xa600
	ds_read_b64_tr_b16 v[190:191], v158 offset:0xae00
	v_cvt_pk_bf16_f32 v117, v74, v75
	v_cvt_pk_bf16_f32 v118, v76, v77
	v_cvt_pk_bf16_f32 v119, v78, v79
	s_nop 1
	v_permlane32_swap_b32_e32 v120, v121
	v_permlane32_swap_b32_e32 v112, v114
	v_permlane32_swap_b32_e32 v113, v115
	v_permlane32_swap_b32_e32 v116, v118
	v_mfma_f32_32x32x16_bf16 v[16:31], v[124:127], v[192:195], v[16:31]
	ds_read_b64_tr_b16 v[192:193], v158 offset:0xb600
	ds_read_b64_tr_b16 v[194:195], v158 offset:0xbe00
	v_permlane32_swap_b32_e32 v117, v119
	ds_write_b128 v157, v[112:115]
	ds_write_b128 v157, v[116:119] offset:1024
	v_add_f32_e32 v120, v120, v121
	v_add_f32_e32 v155, v155, v120
	s_waitcnt lgkmcnt(0)
	v_mfma_f32_32x32x16_bf16 v[0:15], v[176:179], v[180:183], v[0:15]
	v_mfma_f32_32x32x16_bf16 v[0:15], v[168:171], v[184:187], v[0:15]
	v_mfma_f32_32x32x16_bf16 v[0:15], v[172:175], v[188:191], v[0:15]
	v_mfma_f32_32x32x16_bf16 v[0:15], v[124:127], v[192:195], v[0:15]
	s_and_saveexec_b64 s[54:55], s[4:5]
	ds_write_b32 v160, v164 offset:8192
	s_or_b64 exec, exec, s[54:55]
	s_waitcnt vmcnt(0)
	s_waitcnt vmcnt(0) lgkmcnt(0)
	s_barrier
	s_branch .LBB0_733
